# residual epilogue: residual loads run four row steps ahead (freed landing buffers reused) instead of three
# speedup vs baseline: 1.0007x; 1.0007x over previous
; __device__ __forceinline__ unsigned pk2(float lo, float hi) { f32x2 v = {lo, hi}; bf16x2_t b = __builtin_convertvector(v, bf16x2_t); return __builtin_bit_cast(unsigned, b); }
;     __device__ __forceinline__ void operator()(const f32x4 (&acc)[2][2][4][2], const Unit& u, int wr, int wc, int fr, int fq) const {
;     ...
;         for (int q = 0; q < 4; ++q) { const int ai = q >> 1, mh = (q & 1) * 2;
;             u32x4 rh[2][2], rl[2][2];
; #pragma unroll
;             for (int m = 0; m < 2; ++m)
; #pragma unroll
;                 for (int bj = 0; bj < 2; ++bj) { const size_t c = (size_t)(row0 + ai * HALF + (mh + m) * 16) * 1024 + col0 + bj * 32;
;                     if (xin) { rh[m][bj] = __builtin_bit_cast(u32x4, *(const f32x4*)(xin + c)); rl[m][bj] = __builtin_bit_cast(u32x4, *(const f32x4*)(xin + c + 4)); }
;                     else { rh[m][bj] = *(const u32x4*)(hi + c); rl[m][bj] = *(const u32x4*)(lo_in + c); } }
; #pragma unroll
;             for (int m = 0; m < 2; ++m) { const int r = row0 + ai * HALF + (mh + m) * 16; float s = 0.f;
; #pragma unroll
;                 for (int bj = 0; bj < 2; ++bj) { const size_t c = (size_t)r * 1024 + col0 + bj * 32; const u32x4 h = rh[m][bj], l = rl[m][bj]; f32x4 b0, b1;
;                     if (xin) { b0 = __builtin_bit_cast(f32x4, h); b1 = __builtin_bit_cast(f32x4, l); }
;                     else { b0 = (f32x4){__uint_as_float(h.x << 16) + __uint_as_float(l.x << 16), __uint_as_float(h.x & 0xffff0000u) + __uint_as_float(l.x & 0xffff0000u),
;                                         __uint_as_float(h.y << 16) + __uint_as_float(l.y << 16), __uint_as_float(h.y & 0xffff0000u) + __uint_as_float(l.y & 0xffff0000u)};
;                            b1 = (f32x4){__uint_as_float(h.z << 16) + __uint_as_float(l.z << 16), __uint_as_float(h.z & 0xffff0000u) + __uint_as_float(l.z & 0xffff0000u),
;                                         __uint_as_float(h.w << 16) + __uint_as_float(l.w << 16), __uint_as_float(h.w & 0xffff0000u) + __uint_as_float(l.w & 0xffff0000u)}; }
;                     const f32x4 v0 = b0 + acc[ai][bj][mh + m][0] * scale + bv[bj][0], v1 = b1 + acc[ai][bj][mh + m][1] * scale + bv[bj][1];
;                     if (fout) { *(f32x4*)(fout + c) = v0; *(f32x4*)(fout + c + 4) = v1; }
;                     else { const unsigned h0 = pk2(v0[0], v0[1]), h1 = pk2(v0[2], v0[3]), h2 = pk2(v1[0], v1[1]), h3 = pk2(v1[2], v1[3]);
.Lepi3_nobias:
	v_add_u32_e32 v217, 0x0, v212
	global_load_dwordx4 v[148:151], v217, s[78:79]
	global_load_dwordx4 v[152:155], v217, s[26:27]
	global_load_dwordx4 v[156:159], v217, s[78:79] offset:64
	global_load_dwordx4 v[160:163], v217, s[26:27] offset:64
	v_add_u32_e32 v217, 0x8000, v212
	global_load_dwordx4 v[164:167], v217, s[78:79]
	global_load_dwordx4 v[168:171], v217, s[26:27]
	global_load_dwordx4 v[172:175], v217, s[78:79] offset:64
	global_load_dwordx4 v[176:179], v217, s[26:27] offset:64
	v_add_u32_e32 v217, 0x10000, v212
	global_load_dwordx4 v[196:199], v217, s[78:79]
	global_load_dwordx4 v[200:203], v217, s[26:27]
	global_load_dwordx4 v[204:207], v217, s[78:79] offset:64
	global_load_dwordx4 v[208:211], v217, s[26:27] offset:64
	s_waitcnt vmcnt(8)
	v_lshlrev_b32_e32 v218, 16, v148
	v_and_b32_e32 v219, 0xffff0000, v148
	v_lshlrev_b32_e32 v220, 16, v152
	v_and_b32_e32 v221, 0xffff0000, v152
	v_pk_add_f32 v[218:219], v[220:221], v[218:219]
	s_nop 0
	v_pk_fma_f32 v[144:145], s[20:21], v[144:145], v[218:219]
	v_lshlrev_b32_e32 v222, 16, v149
	v_and_b32_e32 v223, 0xffff0000, v149
	v_lshlrev_b32_e32 v250, 16, v153
	v_and_b32_e32 v251, 0xffff0000, v153
	v_pk_add_f32 v[222:223], v[250:251], v[222:223]
	s_nop 0
	v_pk_fma_f32 v[146:147], s[20:21], v[146:147], v[222:223]
	v_lshlrev_b32_e32 v218, 16, v150
	v_and_b32_e32 v219, 0xffff0000, v150
	v_lshlrev_b32_e32 v220, 16, v154
	v_and_b32_e32 v221, 0xffff0000, v154
	v_pk_add_f32 v[218:219], v[220:221], v[218:219]
	s_nop 0
	v_pk_fma_f32 v[140:141], s[20:21], v[140:141], v[218:219]
	v_lshlrev_b32_e32 v222, 16, v151
	v_and_b32_e32 v223, 0xffff0000, v151
	v_lshlrev_b32_e32 v250, 16, v155
	v_and_b32_e32 v251, 0xffff0000, v155
	v_pk_add_f32 v[222:223], v[250:251], v[222:223]
	s_nop 0
	v_pk_fma_f32 v[142:143], s[20:21], v[142:143], v[222:223]
	v_pk_add_f32 v[144:145], v[56:57], v[144:145]
	v_pk_add_f32 v[146:147], v[58:59], v[146:147]
	v_pk_add_f32 v[140:141], v[48:49], v[140:141]
	v_pk_add_f32 v[142:143], v[50:51], v[142:143]
	v_mul_f32_e32 v247, v144, v144
	v_mul_f32_e32 v249, v146, v146
	v_fmac_f32_e32 v247, v145, v145
	v_fmac_f32_e32 v249, v147, v147
	v_mul_f32_e32 v252, v140, v140
	v_add_f32_e32 v247, v247, v249
	v_mul_f32_e32 v249, v142, v142
	v_fmac_f32_e32 v252, v141, v141
	v_fmac_f32_e32 v249, v143, v143
	v_add_f32_e32 v252, v252, v249
	v_add_f32_e32 v247, v247, v252
	v_mov_b32_e32 v213, v247
	v_cvt_pk_bf16_f32 v148, v144, v145
	v_lshlrev_b32_e32 v218, 16, v148
	v_and_b32_e32 v219, 0xffff0000, v148
	v_pk_add_f32 v[144:145], v[144:145], v[218:219] neg_lo:[0,1] neg_hi:[0,1]
	s_nop 0
	v_cvt_pk_bf16_f32 v152, v144, v145
	v_cvt_pk_bf16_f32 v149, v146, v147
	v_lshlrev_b32_e32 v222, 16, v149
	v_and_b32_e32 v223, 0xffff0000, v149
	v_pk_add_f32 v[146:147], v[146:147], v[222:223] neg_lo:[0,1] neg_hi:[0,1]
	s_nop 0
	v_cvt_pk_bf16_f32 v153, v146, v147
	v_cvt_pk_bf16_f32 v150, v140, v141
	v_lshlrev_b32_e32 v218, 16, v150
	v_and_b32_e32 v219, 0xffff0000, v150
	v_pk_add_f32 v[140:141], v[140:141], v[218:219] neg_lo:[0,1] neg_hi:[0,1]
	s_nop 0
	v_cvt_pk_bf16_f32 v154, v140, v141
	v_cvt_pk_bf16_f32 v151, v142, v143
	v_lshlrev_b32_e32 v222, 16, v151
	v_and_b32_e32 v223, 0xffff0000, v151
	v_pk_add_f32 v[142:143], v[142:143], v[222:223] neg_lo:[0,1] neg_hi:[0,1]
	s_nop 0
	v_cvt_pk_bf16_f32 v155, v142, v143
	v_lshlrev_b32_e32 v218, 16, v156
	v_and_b32_e32 v219, 0xffff0000, v156
	v_lshlrev_b32_e32 v220, 16, v160
	v_and_b32_e32 v221, 0xffff0000, v160
	v_pk_add_f32 v[218:219], v[220:221], v[218:219]
	s_nop 0
	v_pk_fma_f32 v[136:137], s[20:21], v[136:137], v[218:219]
	v_lshlrev_b32_e32 v222, 16, v157
	v_and_b32_e32 v223, 0xffff0000, v157
	v_lshlrev_b32_e32 v250, 16, v161
	v_and_b32_e32 v251, 0xffff0000, v161
	v_pk_add_f32 v[222:223], v[250:251], v[222:223]
	s_nop 0
	v_pk_fma_f32 v[138:139], s[20:21], v[138:139], v[222:223]
	v_lshlrev_b32_e32 v218, 16, v158
	v_and_b32_e32 v219, 0xffff0000, v158
	v_lshlrev_b32_e32 v220, 16, v162
	v_and_b32_e32 v221, 0xffff0000, v162
	v_pk_add_f32 v[218:219], v[220:221], v[218:219]
	s_nop 0
	v_pk_fma_f32 v[132:133], s[20:21], v[132:133], v[218:219]
	v_lshlrev_b32_e32 v222, 16, v159
	v_and_b32_e32 v223, 0xffff0000, v159
	v_lshlrev_b32_e32 v250, 16, v163
	v_and_b32_e32 v251, 0xffff0000, v163
	v_pk_add_f32 v[222:223], v[250:251], v[222:223]
	s_nop 0
	v_pk_fma_f32 v[134:135], s[20:21], v[134:135], v[222:223]
	v_pk_add_f32 v[136:137], v[40:41], v[136:137]
	v_pk_add_f32 v[138:139], v[42:43], v[138:139]
	v_pk_add_f32 v[132:133], v[36:37], v[132:133]
	v_pk_add_f32 v[134:135], v[38:39], v[134:135]
	v_mul_f32_e32 v247, v136, v136
	v_mul_f32_e32 v249, v138, v138
	v_fmac_f32_e32 v247, v137, v137
	v_fmac_f32_e32 v249, v139, v139
	v_mul_f32_e32 v252, v132, v132
	v_add_f32_e32 v247, v247, v249
	v_mul_f32_e32 v249, v134, v134
	v_fmac_f32_e32 v252, v133, v133
	v_fmac_f32_e32 v249, v135, v135
	v_add_f32_e32 v252, v252, v249
	v_add_f32_e32 v247, v247, v252
	v_add_f32_e32 v213, v213, v247
	v_cvt_pk_bf16_f32 v156, v136, v137
	v_lshlrev_b32_e32 v218, 16, v156
	v_and_b32_e32 v219, 0xffff0000, v156
	v_pk_add_f32 v[136:137], v[136:137], v[218:219] neg_lo:[0,1] neg_hi:[0,1]
	s_nop 0
	v_cvt_pk_bf16_f32 v160, v136, v137
	v_cvt_pk_bf16_f32 v157, v138, v139
	v_lshlrev_b32_e32 v222, 16, v157
	v_and_b32_e32 v223, 0xffff0000, v157
	v_pk_add_f32 v[138:139], v[138:139], v[222:223] neg_lo:[0,1] neg_hi:[0,1]
	s_nop 0
	v_cvt_pk_bf16_f32 v161, v138, v139
	v_cvt_pk_bf16_f32 v158, v132, v133
	v_lshlrev_b32_e32 v218, 16, v158
	v_and_b32_e32 v219, 0xffff0000, v158
	v_pk_add_f32 v[132:133], v[132:133], v[218:219] neg_lo:[0,1] neg_hi:[0,1]
	s_nop 0
	v_cvt_pk_bf16_f32 v162, v132, v133
	v_cvt_pk_bf16_f32 v159, v134, v135
	v_lshlrev_b32_e32 v222, 16, v159
	v_and_b32_e32 v223, 0xffff0000, v159
	v_pk_add_f32 v[134:135], v[134:135], v[222:223] neg_lo:[0,1] neg_hi:[0,1]
	s_nop 0
	v_cvt_pk_bf16_f32 v163, v134, v135
	v_add_u32_e32 v217, 0x18000, v212
	global_load_dwordx4 v[132:135], v217, s[78:79]
	global_load_dwordx4 v[136:139], v217, s[26:27]
	global_load_dwordx4 v[140:143], v217, s[78:79] offset:64
	global_load_dwordx4 v[144:147], v217, s[26:27] offset:64
	v_add_u32_e32 v245, 0x0, v212
	global_store_dwordx4 v245, v[148:151], s[78:79]
	global_store_dwordx4 v245, v[152:155], s[28:29]
	global_store_dwordx4 v245, v[156:159], s[78:79] offset:64
	global_store_dwordx4 v245, v[160:163], s[28:29] offset:64
	s_waitcnt vmcnt(12)
;     __device__ __forceinline__ void operator()(const f32x4 (&acc)[2][2][4][2], const Unit& u, int wr, int wc, int fr, int fq) const {
;     ...
;             for (int m = 0; m < 2; ++m) { const int r = row0 + ai * HALF + (mh + m) * 16; float s = 0.f;
; #pragma unroll
;                 for (int bj = 0; bj < 2; ++bj) { const size_t c = (size_t)r * 1024 + col0 + bj * 32; const u32x4 h = rh[m][bj], l = rl[m][bj]; f32x4 b0, b1;
;                     if (xin) { b0 = __builtin_bit_cast(f32x4, h); b1 = __builtin_bit_cast(f32x4, l); }
;                     else { b0 = (f32x4){__uint_as_float(h.x << 16) + __uint_as_float(l.x << 16), __uint_as_float(h.x & 0xffff0000u) + __uint_as_float(l.x & 0xffff0000u),
;                                         __uint_as_float(h.y << 16) + __uint_as_float(l.y << 16), __uint_as_float(h.y & 0xffff0000u) + __uint_as_float(l.y & 0xffff0000u)};
;                            b1 = (f32x4){__uint_as_float(h.z << 16) + __uint_as_float(l.z << 16), __uint_as_float(h.z & 0xffff0000u) + __uint_as_float(l.z & 0xffff0000u),
;                                         __uint_as_float(h.w << 16) + __uint_as_float(l.w << 16), __uint_as_float(h.w & 0xffff0000u) + __uint_as_float(l.w & 0xffff0000u)}; }
;                     const f32x4 v0 = b0 + acc[ai][bj][mh + m][0] * scale + bv[bj][0], v1 = b1 + acc[ai][bj][mh + m][1] * scale + bv[bj][1];
;                     if (fout) { *(f32x4*)(fout + c) = v0; *(f32x4*)(fout + c + 4) = v1; }
;                     else { const unsigned h0 = pk2(v0[0], v0[1]), h1 = pk2(v0[2], v0[3]), h2 = pk2(v1[0], v1[1]), h3 = pk2(v1[2], v1[3]);
;                         const unsigned l0 = pk2(v0[0] - __uint_as_float(h0 << 16), v0[1] - __uint_as_float(h0 & 0xffff0000u)), l1 = pk2(v0[2] - __uint_as_float(h1 << 16), v0[3] - __uint_as_float(h1 & 0xffff0000u)),
;                                        l2 = pk2(v1[0] - __uint_as_float(h2 << 16), v1[1] - __uint_as_float(h2 & 0xffff0000u)), l3 = pk2(v1[2] - __uint_as_float(h3 << 16), v1[3] - __uint_as_float(h3 & 0xffff0000u));
;                         *(u32x4*)(hi + c) = (u32x4){h0, h1, h2, h3}; *(u32x4*)(lo_out + c) = (u32x4){l0, l1, l2, l3}; }
;                     s += ((v0[0] * v0[0] + v0[1] * v0[1]) + (v0[2] * v0[2] + v0[3] * v0[3])) + ((v1[0] * v1[0] + v1[1] * v1[1]) + (v1[2] * v1[2] + v1[3] * v1[3])); }
	v_lshlrev_b32_e32 v218, 16, v164
	v_and_b32_e32 v219, 0xffff0000, v164
	v_lshlrev_b32_e32 v220, 16, v168
	v_and_b32_e32 v221, 0xffff0000, v168
	v_pk_add_f32 v[218:219], v[220:221], v[218:219]
	s_nop 0
	v_pk_fma_f32 v[128:129], s[20:21], v[128:129], v[218:219]
	v_lshlrev_b32_e32 v222, 16, v165
	v_and_b32_e32 v223, 0xffff0000, v165
	v_lshlrev_b32_e32 v250, 16, v169
	v_and_b32_e32 v251, 0xffff0000, v169
	v_pk_add_f32 v[222:223], v[250:251], v[222:223]
	s_nop 0
	v_pk_fma_f32 v[130:131], s[20:21], v[130:131], v[222:223]
	v_lshlrev_b32_e32 v218, 16, v166
	v_and_b32_e32 v219, 0xffff0000, v166
	v_lshlrev_b32_e32 v220, 16, v170
	v_and_b32_e32 v221, 0xffff0000, v170
	v_pk_add_f32 v[218:219], v[220:221], v[218:219]
	s_nop 0
	v_pk_fma_f32 v[124:125], s[20:21], v[124:125], v[218:219]
	v_lshlrev_b32_e32 v222, 16, v167
	v_and_b32_e32 v223, 0xffff0000, v167
	v_lshlrev_b32_e32 v250, 16, v171
	v_and_b32_e32 v251, 0xffff0000, v171
	v_pk_add_f32 v[222:223], v[250:251], v[222:223]
	s_nop 0
	v_pk_fma_f32 v[126:127], s[20:21], v[126:127], v[222:223]
	v_pk_add_f32 v[128:129], v[56:57], v[128:129]
	v_pk_add_f32 v[130:131], v[58:59], v[130:131]
	v_pk_add_f32 v[124:125], v[48:49], v[124:125]
	v_pk_add_f32 v[126:127], v[50:51], v[126:127]
	v_mul_f32_e32 v247, v128, v128
	v_mul_f32_e32 v249, v130, v130
	v_fmac_f32_e32 v247, v129, v129
	v_fmac_f32_e32 v249, v131, v131
	v_mul_f32_e32 v252, v124, v124
	v_add_f32_e32 v247, v247, v249
	v_mul_f32_e32 v249, v126, v126
	v_fmac_f32_e32 v252, v125, v125
	v_fmac_f32_e32 v249, v127, v127
	v_add_f32_e32 v252, v252, v249
	v_add_f32_e32 v247, v247, v252
	v_mov_b32_e32 v148, v247
	v_cvt_pk_bf16_f32 v164, v128, v129
	v_lshlrev_b32_e32 v218, 16, v164
	v_and_b32_e32 v219, 0xffff0000, v164
	v_pk_add_f32 v[128:129], v[128:129], v[218:219] neg_lo:[0,1] neg_hi:[0,1]
	s_nop 0
	v_cvt_pk_bf16_f32 v168, v128, v129
	v_cvt_pk_bf16_f32 v165, v130, v131
	v_lshlrev_b32_e32 v222, 16, v165
	v_and_b32_e32 v223, 0xffff0000, v165
	v_pk_add_f32 v[130:131], v[130:131], v[222:223] neg_lo:[0,1] neg_hi:[0,1]
	s_nop 0
	v_cvt_pk_bf16_f32 v169, v130, v131
	v_cvt_pk_bf16_f32 v166, v124, v125
	v_lshlrev_b32_e32 v218, 16, v166
	v_and_b32_e32 v219, 0xffff0000, v166
	v_pk_add_f32 v[124:125], v[124:125], v[218:219] neg_lo:[0,1] neg_hi:[0,1]
	s_nop 0
	v_cvt_pk_bf16_f32 v170, v124, v125
	v_cvt_pk_bf16_f32 v167, v126, v127
	v_lshlrev_b32_e32 v222, 16, v167
	v_and_b32_e32 v223, 0xffff0000, v167
	v_pk_add_f32 v[126:127], v[126:127], v[222:223] neg_lo:[0,1] neg_hi:[0,1]
	s_nop 0
	v_cvt_pk_bf16_f32 v171, v126, v127
	v_lshlrev_b32_e32 v218, 16, v172
	v_and_b32_e32 v219, 0xffff0000, v172
	v_lshlrev_b32_e32 v220, 16, v176
	v_and_b32_e32 v221, 0xffff0000, v176
	v_pk_add_f32 v[218:219], v[220:221], v[218:219]
	s_nop 0
	v_pk_fma_f32 v[120:121], s[20:21], v[120:121], v[218:219]
	v_lshlrev_b32_e32 v222, 16, v173
	v_and_b32_e32 v223, 0xffff0000, v173
	v_lshlrev_b32_e32 v250, 16, v177
	v_and_b32_e32 v251, 0xffff0000, v177
	v_pk_add_f32 v[222:223], v[250:251], v[222:223]
	s_nop 0
	v_pk_fma_f32 v[122:123], s[20:21], v[122:123], v[222:223]
	v_lshlrev_b32_e32 v218, 16, v174
	v_and_b32_e32 v219, 0xffff0000, v174
	v_lshlrev_b32_e32 v220, 16, v178
	v_and_b32_e32 v221, 0xffff0000, v178
	v_pk_add_f32 v[218:219], v[220:221], v[218:219]
	s_nop 0
	v_pk_fma_f32 v[116:117], s[20:21], v[116:117], v[218:219]
	v_lshlrev_b32_e32 v222, 16, v175
	v_and_b32_e32 v223, 0xffff0000, v175
	v_lshlrev_b32_e32 v250, 16, v179
	v_and_b32_e32 v251, 0xffff0000, v179
	v_pk_add_f32 v[222:223], v[250:251], v[222:223]
	s_nop 0
	v_pk_fma_f32 v[118:119], s[20:21], v[118:119], v[222:223]
	v_pk_add_f32 v[120:121], v[40:41], v[120:121]
	v_pk_add_f32 v[122:123], v[42:43], v[122:123]
	v_pk_add_f32 v[116:117], v[36:37], v[116:117]
	v_pk_add_f32 v[118:119], v[38:39], v[118:119]
	v_mul_f32_e32 v247, v120, v120
	v_mul_f32_e32 v249, v122, v122
	v_fmac_f32_e32 v247, v121, v121
	v_fmac_f32_e32 v249, v123, v123
	v_mul_f32_e32 v252, v116, v116
	v_add_f32_e32 v247, v247, v249
	v_mul_f32_e32 v249, v118, v118
	v_fmac_f32_e32 v252, v117, v117
	v_fmac_f32_e32 v249, v119, v119
	v_add_f32_e32 v252, v252, v249
	v_add_f32_e32 v247, v247, v252
	v_add_f32_e32 v148, v148, v247
	v_cvt_pk_bf16_f32 v172, v120, v121
	v_lshlrev_b32_e32 v218, 16, v172
	v_and_b32_e32 v219, 0xffff0000, v172
	v_pk_add_f32 v[120:121], v[120:121], v[218:219] neg_lo:[0,1] neg_hi:[0,1]
	s_nop 0
	v_cvt_pk_bf16_f32 v176, v120, v121
	v_cvt_pk_bf16_f32 v173, v122, v123
	v_lshlrev_b32_e32 v222, 16, v173
	v_and_b32_e32 v223, 0xffff0000, v173
	v_pk_add_f32 v[122:123], v[122:123], v[222:223] neg_lo:[0,1] neg_hi:[0,1]
	s_nop 0
	v_cvt_pk_bf16_f32 v177, v122, v123
	v_cvt_pk_bf16_f32 v174, v116, v117
	v_lshlrev_b32_e32 v218, 16, v174
	v_and_b32_e32 v219, 0xffff0000, v174
	v_pk_add_f32 v[116:117], v[116:117], v[218:219] neg_lo:[0,1] neg_hi:[0,1]
	s_nop 0
	v_cvt_pk_bf16_f32 v178, v116, v117
	v_cvt_pk_bf16_f32 v175, v118, v119
	v_lshlrev_b32_e32 v222, 16, v175
	v_and_b32_e32 v223, 0xffff0000, v175
	v_pk_add_f32 v[118:119], v[118:119], v[222:223] neg_lo:[0,1] neg_hi:[0,1]
	s_nop 0
	v_cvt_pk_bf16_f32 v179, v118, v119
	v_add_u32_e32 v217, 0x40000, v212
	global_load_dwordx4 v[116:119], v217, s[78:79]
	global_load_dwordx4 v[120:123], v217, s[26:27]
	global_load_dwordx4 v[124:127], v217, s[78:79] offset:64
	global_load_dwordx4 v[128:131], v217, s[26:27] offset:64
	v_add_u32_e32 v245, 0x8000, v212
	global_store_dwordx4 v245, v[164:167], s[78:79]
	global_store_dwordx4 v245, v[168:171], s[28:29]
	global_store_dwordx4 v245, v[172:175], s[78:79] offset:64
	global_store_dwordx4 v245, v[176:179], s[28:29] offset:64
	s_waitcnt vmcnt(16)
;     __device__ __forceinline__ void operator()(const f32x4 (&acc)[2][2][4][2], const Unit& u, int wr, int wc, int fr, int fq) const {
;     ...
;             for (int m = 0; m < 2; ++m) { const int r = row0 + ai * HALF + (mh + m) * 16; float s = 0.f;
; #pragma unroll
;                 for (int bj = 0; bj < 2; ++bj) { const size_t c = (size_t)r * 1024 + col0 + bj * 32; const u32x4 h = rh[m][bj], l = rl[m][bj]; f32x4 b0, b1;
;                     if (xin) { b0 = __builtin_bit_cast(f32x4, h); b1 = __builtin_bit_cast(f32x4, l); }
;                     else { b0 = (f32x4){__uint_as_float(h.x << 16) + __uint_as_float(l.x << 16), __uint_as_float(h.x & 0xffff0000u) + __uint_as_float(l.x & 0xffff0000u),
;                                         __uint_as_float(h.y << 16) + __uint_as_float(l.y << 16), __uint_as_float(h.y & 0xffff0000u) + __uint_as_float(l.y & 0xffff0000u)};
;                            b1 = (f32x4){__uint_as_float(h.z << 16) + __uint_as_float(l.z << 16), __uint_as_float(h.z & 0xffff0000u) + __uint_as_float(l.z & 0xffff0000u),
;                                         __uint_as_float(h.w << 16) + __uint_as_float(l.w << 16), __uint_as_float(h.w & 0xffff0000u) + __uint_as_float(l.w & 0xffff0000u)}; }
;                     const f32x4 v0 = b0 + acc[ai][bj][mh + m][0] * scale + bv[bj][0], v1 = b1 + acc[ai][bj][mh + m][1] * scale + bv[bj][1];
;                     if (fout) { *(f32x4*)(fout + c) = v0; *(f32x4*)(fout + c + 4) = v1; }
;                     else { const unsigned h0 = pk2(v0[0], v0[1]), h1 = pk2(v0[2], v0[3]), h2 = pk2(v1[0], v1[1]), h3 = pk2(v1[2], v1[3]);
;                         const unsigned l0 = pk2(v0[0] - __uint_as_float(h0 << 16), v0[1] - __uint_as_float(h0 & 0xffff0000u)), l1 = pk2(v0[2] - __uint_as_float(h1 << 16), v0[3] - __uint_as_float(h1 & 0xffff0000u)),
;                                        l2 = pk2(v1[0] - __uint_as_float(h2 << 16), v1[1] - __uint_as_float(h2 & 0xffff0000u)), l3 = pk2(v1[2] - __uint_as_float(h3 << 16), v1[3] - __uint_as_float(h3 & 0xffff0000u));
;                         *(u32x4*)(hi + c) = (u32x4){h0, h1, h2, h3}; *(u32x4*)(lo_out + c) = (u32x4){l0, l1, l2, l3}; }
;                     s += ((v0[0] * v0[0] + v0[1] * v0[1]) + (v0[2] * v0[2] + v0[3] * v0[3])) + ((v1[0] * v1[0] + v1[1] * v1[1]) + (v1[2] * v1[2] + v1[3] * v1[3])); }
	v_lshlrev_b32_e32 v218, 16, v196
	v_and_b32_e32 v219, 0xffff0000, v196
	v_lshlrev_b32_e32 v220, 16, v200
	v_and_b32_e32 v221, 0xffff0000, v200
	v_pk_add_f32 v[218:219], v[220:221], v[218:219]
	s_nop 0
	v_pk_fma_f32 v[112:113], s[20:21], v[112:113], v[218:219]
	v_lshlrev_b32_e32 v222, 16, v197
	v_and_b32_e32 v223, 0xffff0000, v197
	v_lshlrev_b32_e32 v250, 16, v201
	v_and_b32_e32 v251, 0xffff0000, v201
	v_pk_add_f32 v[222:223], v[250:251], v[222:223]
	s_nop 0
	v_pk_fma_f32 v[114:115], s[20:21], v[114:115], v[222:223]
	v_lshlrev_b32_e32 v218, 16, v198
	v_and_b32_e32 v219, 0xffff0000, v198
	v_lshlrev_b32_e32 v220, 16, v202
	v_and_b32_e32 v221, 0xffff0000, v202
	v_pk_add_f32 v[218:219], v[220:221], v[218:219]
	s_nop 0
	v_pk_fma_f32 v[108:109], s[20:21], v[108:109], v[218:219]
	v_lshlrev_b32_e32 v222, 16, v199
	v_and_b32_e32 v223, 0xffff0000, v199
	v_lshlrev_b32_e32 v250, 16, v203
	v_and_b32_e32 v251, 0xffff0000, v203
	v_pk_add_f32 v[222:223], v[250:251], v[222:223]
	s_nop 0
	v_pk_fma_f32 v[110:111], s[20:21], v[110:111], v[222:223]
	v_pk_add_f32 v[112:113], v[56:57], v[112:113]
	v_pk_add_f32 v[114:115], v[58:59], v[114:115]
	v_pk_add_f32 v[108:109], v[48:49], v[108:109]
	v_pk_add_f32 v[110:111], v[50:51], v[110:111]
	v_mul_f32_e32 v247, v112, v112
	v_mul_f32_e32 v249, v114, v114
	v_fmac_f32_e32 v247, v113, v113
	v_fmac_f32_e32 v249, v115, v115
	v_mul_f32_e32 v252, v108, v108
	v_add_f32_e32 v247, v247, v249
	v_mul_f32_e32 v249, v110, v110
	v_fmac_f32_e32 v252, v109, v109
	v_fmac_f32_e32 v249, v111, v111
	v_add_f32_e32 v252, v252, v249
	v_add_f32_e32 v247, v247, v252
	v_mov_b32_e32 v149, v247
	v_cvt_pk_bf16_f32 v196, v112, v113
	v_lshlrev_b32_e32 v218, 16, v196
	v_and_b32_e32 v219, 0xffff0000, v196
	v_pk_add_f32 v[112:113], v[112:113], v[218:219] neg_lo:[0,1] neg_hi:[0,1]
	s_nop 0
	v_cvt_pk_bf16_f32 v200, v112, v113
	v_cvt_pk_bf16_f32 v197, v114, v115
	v_lshlrev_b32_e32 v222, 16, v197
	v_and_b32_e32 v223, 0xffff0000, v197
	v_pk_add_f32 v[114:115], v[114:115], v[222:223] neg_lo:[0,1] neg_hi:[0,1]
	s_nop 0
	v_cvt_pk_bf16_f32 v201, v114, v115
	v_cvt_pk_bf16_f32 v198, v108, v109
	v_lshlrev_b32_e32 v218, 16, v198
	v_and_b32_e32 v219, 0xffff0000, v198
	v_pk_add_f32 v[108:109], v[108:109], v[218:219] neg_lo:[0,1] neg_hi:[0,1]
	s_nop 0
	v_cvt_pk_bf16_f32 v202, v108, v109
	v_cvt_pk_bf16_f32 v199, v110, v111
	v_lshlrev_b32_e32 v222, 16, v199
	v_and_b32_e32 v223, 0xffff0000, v199
	v_pk_add_f32 v[110:111], v[110:111], v[222:223] neg_lo:[0,1] neg_hi:[0,1]
	s_nop 0
	v_cvt_pk_bf16_f32 v203, v110, v111
	v_lshlrev_b32_e32 v218, 16, v204
	v_and_b32_e32 v219, 0xffff0000, v204
	v_lshlrev_b32_e32 v220, 16, v208
	v_and_b32_e32 v221, 0xffff0000, v208
	v_pk_add_f32 v[218:219], v[220:221], v[218:219]
	s_nop 0
	v_pk_fma_f32 v[104:105], s[20:21], v[104:105], v[218:219]
	v_lshlrev_b32_e32 v222, 16, v205
	v_and_b32_e32 v223, 0xffff0000, v205
	v_lshlrev_b32_e32 v250, 16, v209
	v_and_b32_e32 v251, 0xffff0000, v209
	v_pk_add_f32 v[222:223], v[250:251], v[222:223]
	s_nop 0
	v_pk_fma_f32 v[106:107], s[20:21], v[106:107], v[222:223]
	v_lshlrev_b32_e32 v218, 16, v206
	v_and_b32_e32 v219, 0xffff0000, v206
	v_lshlrev_b32_e32 v220, 16, v210
	v_and_b32_e32 v221, 0xffff0000, v210
	v_pk_add_f32 v[218:219], v[220:221], v[218:219]
	s_nop 0
	v_pk_fma_f32 v[100:101], s[20:21], v[100:101], v[218:219]
	v_lshlrev_b32_e32 v222, 16, v207
	v_and_b32_e32 v223, 0xffff0000, v207
	v_lshlrev_b32_e32 v250, 16, v211
	v_and_b32_e32 v251, 0xffff0000, v211
	v_pk_add_f32 v[222:223], v[250:251], v[222:223]
	s_nop 0
	v_pk_fma_f32 v[102:103], s[20:21], v[102:103], v[222:223]
	v_pk_add_f32 v[104:105], v[40:41], v[104:105]
	v_pk_add_f32 v[106:107], v[42:43], v[106:107]
	v_pk_add_f32 v[100:101], v[36:37], v[100:101]
	v_pk_add_f32 v[102:103], v[38:39], v[102:103]
	v_mul_f32_e32 v247, v104, v104
	v_mul_f32_e32 v249, v106, v106
	v_fmac_f32_e32 v247, v105, v105
	v_fmac_f32_e32 v249, v107, v107
	v_mul_f32_e32 v252, v100, v100
	v_add_f32_e32 v247, v247, v249
	v_mul_f32_e32 v249, v102, v102
	v_fmac_f32_e32 v252, v101, v101
	v_fmac_f32_e32 v249, v103, v103
	v_add_f32_e32 v252, v252, v249
	v_add_f32_e32 v247, v247, v252
	v_add_f32_e32 v149, v149, v247
	v_cvt_pk_bf16_f32 v204, v104, v105
	v_lshlrev_b32_e32 v218, 16, v204
	v_and_b32_e32 v219, 0xffff0000, v204
	v_pk_add_f32 v[104:105], v[104:105], v[218:219] neg_lo:[0,1] neg_hi:[0,1]
	s_nop 0
	v_cvt_pk_bf16_f32 v208, v104, v105
	v_cvt_pk_bf16_f32 v205, v106, v107
	v_lshlrev_b32_e32 v222, 16, v205
	v_and_b32_e32 v223, 0xffff0000, v205
	v_pk_add_f32 v[106:107], v[106:107], v[222:223] neg_lo:[0,1] neg_hi:[0,1]
	s_nop 0
	v_cvt_pk_bf16_f32 v209, v106, v107
	v_cvt_pk_bf16_f32 v206, v100, v101
	v_lshlrev_b32_e32 v218, 16, v206
	v_and_b32_e32 v219, 0xffff0000, v206
	v_pk_add_f32 v[100:101], v[100:101], v[218:219] neg_lo:[0,1] neg_hi:[0,1]
	s_nop 0
	v_cvt_pk_bf16_f32 v210, v100, v101
	v_cvt_pk_bf16_f32 v207, v102, v103
	v_lshlrev_b32_e32 v222, 16, v207
	v_and_b32_e32 v223, 0xffff0000, v207
	v_pk_add_f32 v[102:103], v[102:103], v[222:223] neg_lo:[0,1] neg_hi:[0,1]
	s_nop 0
	v_cvt_pk_bf16_f32 v211, v102, v103
	v_add_u32_e32 v217, 0x48000, v212
	global_load_dwordx4 v[164:167], v217, s[78:79]
	global_load_dwordx4 v[168:171], v217, s[26:27]
	global_load_dwordx4 v[172:175], v217, s[78:79] offset:64
	global_load_dwordx4 v[176:179], v217, s[26:27] offset:64
	v_add_u32_e32 v217, 0x50000, v212
	global_load_dwordx4 v[100:103], v217, s[78:79]
	global_load_dwordx4 v[104:107], v217, s[26:27]
	global_load_dwordx4 v[108:111], v217, s[78:79] offset:64
	global_load_dwordx4 v[112:115], v217, s[26:27] offset:64
	v_add_u32_e32 v245, 0x10000, v212
	global_store_dwordx4 v245, v[196:199], s[78:79]
	global_store_dwordx4 v245, v[200:203], s[28:29]
	global_store_dwordx4 v245, v[204:207], s[78:79] offset:64
	global_store_dwordx4 v245, v[208:211], s[28:29] offset:64
	s_waitcnt vmcnt(24)
;     __device__ __forceinline__ void operator()(const f32x4 (&acc)[2][2][4][2], const Unit& u, int wr, int wc, int fr, int fq) const {
;     ...
;             for (int m = 0; m < 2; ++m) { const int r = row0 + ai * HALF + (mh + m) * 16; float s = 0.f;
; #pragma unroll
;                 for (int bj = 0; bj < 2; ++bj) { const size_t c = (size_t)r * 1024 + col0 + bj * 32; const u32x4 h = rh[m][bj], l = rl[m][bj]; f32x4 b0, b1;
;                     if (xin) { b0 = __builtin_bit_cast(f32x4, h); b1 = __builtin_bit_cast(f32x4, l); }
;                     else { b0 = (f32x4){__uint_as_float(h.x << 16) + __uint_as_float(l.x << 16), __uint_as_float(h.x & 0xffff0000u) + __uint_as_float(l.x & 0xffff0000u),
;                                         __uint_as_float(h.y << 16) + __uint_as_float(l.y << 16), __uint_as_float(h.y & 0xffff0000u) + __uint_as_float(l.y & 0xffff0000u)};
;                            b1 = (f32x4){__uint_as_float(h.z << 16) + __uint_as_float(l.z << 16), __uint_as_float(h.z & 0xffff0000u) + __uint_as_float(l.z & 0xffff0000u),
;                                         __uint_as_float(h.w << 16) + __uint_as_float(l.w << 16), __uint_as_float(h.w & 0xffff0000u) + __uint_as_float(l.w & 0xffff0000u)}; }
;                     const f32x4 v0 = b0 + acc[ai][bj][mh + m][0] * scale + bv[bj][0], v1 = b1 + acc[ai][bj][mh + m][1] * scale + bv[bj][1];
;                     if (fout) { *(f32x4*)(fout + c) = v0; *(f32x4*)(fout + c + 4) = v1; }
;                     else { const unsigned h0 = pk2(v0[0], v0[1]), h1 = pk2(v0[2], v0[3]), h2 = pk2(v1[0], v1[1]), h3 = pk2(v1[2], v1[3]);
;                         const unsigned l0 = pk2(v0[0] - __uint_as_float(h0 << 16), v0[1] - __uint_as_float(h0 & 0xffff0000u)), l1 = pk2(v0[2] - __uint_as_float(h1 << 16), v0[3] - __uint_as_float(h1 & 0xffff0000u)),
;                                        l2 = pk2(v1[0] - __uint_as_float(h2 << 16), v1[1] - __uint_as_float(h2 & 0xffff0000u)), l3 = pk2(v1[2] - __uint_as_float(h3 << 16), v1[3] - __uint_as_float(h3 & 0xffff0000u));
;                         *(u32x4*)(hi + c) = (u32x4){h0, h1, h2, h3}; *(u32x4*)(lo_out + c) = (u32x4){l0, l1, l2, l3}; }
;                     s += ((v0[0] * v0[0] + v0[1] * v0[1]) + (v0[2] * v0[2] + v0[3] * v0[3])) + ((v1[0] * v1[0] + v1[1] * v1[1]) + (v1[2] * v1[2] + v1[3] * v1[3])); }
	v_lshlrev_b32_e32 v218, 16, v132
	v_and_b32_e32 v219, 0xffff0000, v132
	v_lshlrev_b32_e32 v220, 16, v136
	v_and_b32_e32 v221, 0xffff0000, v136
	v_pk_add_f32 v[218:219], v[220:221], v[218:219]
	s_nop 0
	v_pk_fma_f32 v[96:97], s[20:21], v[96:97], v[218:219]
	v_lshlrev_b32_e32 v222, 16, v133
	v_and_b32_e32 v223, 0xffff0000, v133
	v_lshlrev_b32_e32 v250, 16, v137
	v_and_b32_e32 v251, 0xffff0000, v137
	v_pk_add_f32 v[222:223], v[250:251], v[222:223]
	s_nop 0
	v_pk_fma_f32 v[98:99], s[20:21], v[98:99], v[222:223]
	v_lshlrev_b32_e32 v218, 16, v134
	v_and_b32_e32 v219, 0xffff0000, v134
	v_lshlrev_b32_e32 v220, 16, v138
	v_and_b32_e32 v221, 0xffff0000, v138
	v_pk_add_f32 v[218:219], v[220:221], v[218:219]
	s_nop 0
	v_pk_fma_f32 v[92:93], s[20:21], v[92:93], v[218:219]
	v_lshlrev_b32_e32 v222, 16, v135
	v_and_b32_e32 v223, 0xffff0000, v135
	v_lshlrev_b32_e32 v250, 16, v139
	v_and_b32_e32 v251, 0xffff0000, v139
	v_pk_add_f32 v[222:223], v[250:251], v[222:223]
	s_nop 0
	v_pk_fma_f32 v[94:95], s[20:21], v[94:95], v[222:223]
	v_pk_add_f32 v[96:97], v[56:57], v[96:97]
	v_pk_add_f32 v[98:99], v[58:59], v[98:99]
	v_pk_add_f32 v[92:93], v[48:49], v[92:93]
	v_pk_add_f32 v[94:95], v[50:51], v[94:95]
	v_mul_f32_e32 v247, v96, v96
	v_mul_f32_e32 v249, v98, v98
	v_fmac_f32_e32 v247, v97, v97
	v_fmac_f32_e32 v249, v99, v99
	v_mul_f32_e32 v252, v92, v92
	v_add_f32_e32 v247, v247, v249
	v_mul_f32_e32 v249, v94, v94
	v_fmac_f32_e32 v252, v93, v93
	v_fmac_f32_e32 v249, v95, v95
	v_add_f32_e32 v252, v252, v249
	v_add_f32_e32 v247, v247, v252
	v_mov_b32_e32 v150, v247
	v_cvt_pk_bf16_f32 v132, v96, v97
	v_lshlrev_b32_e32 v218, 16, v132
	v_and_b32_e32 v219, 0xffff0000, v132
	v_pk_add_f32 v[96:97], v[96:97], v[218:219] neg_lo:[0,1] neg_hi:[0,1]
	s_nop 0
	v_cvt_pk_bf16_f32 v136, v96, v97
	v_cvt_pk_bf16_f32 v133, v98, v99
	v_lshlrev_b32_e32 v222, 16, v133
	v_and_b32_e32 v223, 0xffff0000, v133
	v_pk_add_f32 v[98:99], v[98:99], v[222:223] neg_lo:[0,1] neg_hi:[0,1]
	s_nop 0
	v_cvt_pk_bf16_f32 v137, v98, v99
	v_cvt_pk_bf16_f32 v134, v92, v93
	v_lshlrev_b32_e32 v218, 16, v134
	v_and_b32_e32 v219, 0xffff0000, v134
	v_pk_add_f32 v[92:93], v[92:93], v[218:219] neg_lo:[0,1] neg_hi:[0,1]
	s_nop 0
	v_cvt_pk_bf16_f32 v138, v92, v93
	v_cvt_pk_bf16_f32 v135, v94, v95
	v_lshlrev_b32_e32 v222, 16, v135
	v_and_b32_e32 v223, 0xffff0000, v135
	v_pk_add_f32 v[94:95], v[94:95], v[222:223] neg_lo:[0,1] neg_hi:[0,1]
	s_nop 0
	v_cvt_pk_bf16_f32 v139, v94, v95
	v_lshlrev_b32_e32 v218, 16, v140
	v_and_b32_e32 v219, 0xffff0000, v140
	v_lshlrev_b32_e32 v220, 16, v144
	v_and_b32_e32 v221, 0xffff0000, v144
	v_pk_add_f32 v[218:219], v[220:221], v[218:219]
	s_nop 0
	v_pk_fma_f32 v[88:89], s[20:21], v[88:89], v[218:219]
	v_lshlrev_b32_e32 v222, 16, v141
	v_and_b32_e32 v223, 0xffff0000, v141
	v_lshlrev_b32_e32 v250, 16, v145
	v_and_b32_e32 v251, 0xffff0000, v145
	v_pk_add_f32 v[222:223], v[250:251], v[222:223]
	s_nop 0
	v_pk_fma_f32 v[90:91], s[20:21], v[90:91], v[222:223]
	v_lshlrev_b32_e32 v218, 16, v142
	v_and_b32_e32 v219, 0xffff0000, v142
	v_lshlrev_b32_e32 v220, 16, v146
	v_and_b32_e32 v221, 0xffff0000, v146
	v_pk_add_f32 v[218:219], v[220:221], v[218:219]
	s_nop 0
	v_pk_fma_f32 v[84:85], s[20:21], v[84:85], v[218:219]
	v_lshlrev_b32_e32 v222, 16, v143
	v_and_b32_e32 v223, 0xffff0000, v143
	v_lshlrev_b32_e32 v250, 16, v147
	v_and_b32_e32 v251, 0xffff0000, v147
	v_pk_add_f32 v[222:223], v[250:251], v[222:223]
	s_nop 0
	v_pk_fma_f32 v[86:87], s[20:21], v[86:87], v[222:223]
	v_pk_add_f32 v[88:89], v[40:41], v[88:89]
	v_pk_add_f32 v[90:91], v[42:43], v[90:91]
	v_pk_add_f32 v[84:85], v[36:37], v[84:85]
	v_pk_add_f32 v[86:87], v[38:39], v[86:87]
	v_mul_f32_e32 v247, v88, v88
	v_mul_f32_e32 v249, v90, v90
	v_fmac_f32_e32 v247, v89, v89
	v_fmac_f32_e32 v249, v91, v91
	v_mul_f32_e32 v252, v84, v84
	v_add_f32_e32 v247, v247, v249
	v_mul_f32_e32 v249, v86, v86
	v_fmac_f32_e32 v252, v85, v85
	v_fmac_f32_e32 v249, v87, v87
	v_add_f32_e32 v252, v252, v249
	v_add_f32_e32 v247, v247, v252
	v_add_f32_e32 v150, v150, v247
	v_cvt_pk_bf16_f32 v140, v88, v89
	v_lshlrev_b32_e32 v218, 16, v140
	v_and_b32_e32 v219, 0xffff0000, v140
	v_pk_add_f32 v[88:89], v[88:89], v[218:219] neg_lo:[0,1] neg_hi:[0,1]
	s_nop 0
	v_cvt_pk_bf16_f32 v144, v88, v89
	v_cvt_pk_bf16_f32 v141, v90, v91
	v_lshlrev_b32_e32 v222, 16, v141
	v_and_b32_e32 v223, 0xffff0000, v141
	v_pk_add_f32 v[90:91], v[90:91], v[222:223] neg_lo:[0,1] neg_hi:[0,1]
	s_nop 0
	v_cvt_pk_bf16_f32 v145, v90, v91
	v_cvt_pk_bf16_f32 v142, v84, v85
	v_lshlrev_b32_e32 v218, 16, v142
	v_and_b32_e32 v219, 0xffff0000, v142
	v_pk_add_f32 v[84:85], v[84:85], v[218:219] neg_lo:[0,1] neg_hi:[0,1]
	s_nop 0
	v_cvt_pk_bf16_f32 v146, v84, v85
	v_cvt_pk_bf16_f32 v143, v86, v87
	v_lshlrev_b32_e32 v222, 16, v143
	v_and_b32_e32 v223, 0xffff0000, v143
	v_pk_add_f32 v[86:87], v[86:87], v[222:223] neg_lo:[0,1] neg_hi:[0,1]
	s_nop 0
	v_cvt_pk_bf16_f32 v147, v86, v87
	v_add_u32_e32 v217, 0x58000, v212
	global_load_dwordx4 v[196:199], v217, s[78:79]
	global_load_dwordx4 v[200:203], v217, s[26:27]
	global_load_dwordx4 v[204:207], v217, s[78:79] offset:64
	global_load_dwordx4 v[208:211], v217, s[26:27] offset:64
	v_add_u32_e32 v245, 0x18000, v212
	global_store_dwordx4 v245, v[132:135], s[78:79]
	global_store_dwordx4 v245, v[136:139], s[28:29]
	global_store_dwordx4 v245, v[140:143], s[78:79] offset:64
	global_store_dwordx4 v245, v[144:147], s[28:29] offset:64
	s_waitcnt vmcnt(24)
;     __device__ __forceinline__ void operator()(const f32x4 (&acc)[2][2][4][2], const Unit& u, int wr, int wc, int fr, int fq) const {
;     ...
;             for (int m = 0; m < 2; ++m) { const int r = row0 + ai * HALF + (mh + m) * 16; float s = 0.f;
; #pragma unroll
;                 for (int bj = 0; bj < 2; ++bj) { const size_t c = (size_t)r * 1024 + col0 + bj * 32; const u32x4 h = rh[m][bj], l = rl[m][bj]; f32x4 b0, b1;
;                     if (xin) { b0 = __builtin_bit_cast(f32x4, h); b1 = __builtin_bit_cast(f32x4, l); }
;                     else { b0 = (f32x4){__uint_as_float(h.x << 16) + __uint_as_float(l.x << 16), __uint_as_float(h.x & 0xffff0000u) + __uint_as_float(l.x & 0xffff0000u),
;                                         __uint_as_float(h.y << 16) + __uint_as_float(l.y << 16), __uint_as_float(h.y & 0xffff0000u) + __uint_as_float(l.y & 0xffff0000u)};
;                            b1 = (f32x4){__uint_as_float(h.z << 16) + __uint_as_float(l.z << 16), __uint_as_float(h.z & 0xffff0000u) + __uint_as_float(l.z & 0xffff0000u),
;                                         __uint_as_float(h.w << 16) + __uint_as_float(l.w << 16), __uint_as_float(h.w & 0xffff0000u) + __uint_as_float(l.w & 0xffff0000u)}; }
;                     const f32x4 v0 = b0 + acc[ai][bj][mh + m][0] * scale + bv[bj][0], v1 = b1 + acc[ai][bj][mh + m][1] * scale + bv[bj][1];
;                     if (fout) { *(f32x4*)(fout + c) = v0; *(f32x4*)(fout + c + 4) = v1; }
;                     else { const unsigned h0 = pk2(v0[0], v0[1]), h1 = pk2(v0[2], v0[3]), h2 = pk2(v1[0], v1[1]), h3 = pk2(v1[2], v1[3]);
;                         const unsigned l0 = pk2(v0[0] - __uint_as_float(h0 << 16), v0[1] - __uint_as_float(h0 & 0xffff0000u)), l1 = pk2(v0[2] - __uint_as_float(h1 << 16), v0[3] - __uint_as_float(h1 & 0xffff0000u)),
;                                        l2 = pk2(v1[0] - __uint_as_float(h2 << 16), v1[1] - __uint_as_float(h2 & 0xffff0000u)), l3 = pk2(v1[2] - __uint_as_float(h3 << 16), v1[3] - __uint_as_float(h3 & 0xffff0000u));
;                         *(u32x4*)(hi + c) = (u32x4){h0, h1, h2, h3}; *(u32x4*)(lo_out + c) = (u32x4){l0, l1, l2, l3}; }
;                     s += ((v0[0] * v0[0] + v0[1] * v0[1]) + (v0[2] * v0[2] + v0[3] * v0[3])) + ((v1[0] * v1[0] + v1[1] * v1[1]) + (v1[2] * v1[2] + v1[3] * v1[3])); }
	v_lshlrev_b32_e32 v218, 16, v116
	v_and_b32_e32 v219, 0xffff0000, v116
	v_lshlrev_b32_e32 v220, 16, v120
	v_and_b32_e32 v221, 0xffff0000, v120
	v_pk_add_f32 v[218:219], v[220:221], v[218:219]
	s_nop 0
	v_pk_fma_f32 v[80:81], s[20:21], v[80:81], v[218:219]
	v_lshlrev_b32_e32 v222, 16, v117
	v_and_b32_e32 v223, 0xffff0000, v117
	v_lshlrev_b32_e32 v250, 16, v121
	v_and_b32_e32 v251, 0xffff0000, v121
	v_pk_add_f32 v[222:223], v[250:251], v[222:223]
	s_nop 0
	v_pk_fma_f32 v[82:83], s[20:21], v[82:83], v[222:223]
	v_lshlrev_b32_e32 v218, 16, v118
	v_and_b32_e32 v219, 0xffff0000, v118
	v_lshlrev_b32_e32 v220, 16, v122
	v_and_b32_e32 v221, 0xffff0000, v122
	v_pk_add_f32 v[218:219], v[220:221], v[218:219]
	s_nop 0
	v_pk_fma_f32 v[76:77], s[20:21], v[76:77], v[218:219]
	v_lshlrev_b32_e32 v222, 16, v119
	v_and_b32_e32 v223, 0xffff0000, v119
	v_lshlrev_b32_e32 v250, 16, v123
	v_and_b32_e32 v251, 0xffff0000, v123
	v_pk_add_f32 v[222:223], v[250:251], v[222:223]
	s_nop 0
	v_pk_fma_f32 v[78:79], s[20:21], v[78:79], v[222:223]
	v_pk_add_f32 v[80:81], v[56:57], v[80:81]
	v_pk_add_f32 v[82:83], v[58:59], v[82:83]
	v_pk_add_f32 v[76:77], v[48:49], v[76:77]
	v_pk_add_f32 v[78:79], v[50:51], v[78:79]
	v_mul_f32_e32 v247, v80, v80
	v_mul_f32_e32 v249, v82, v82
	v_fmac_f32_e32 v247, v81, v81
	v_fmac_f32_e32 v249, v83, v83
	v_mul_f32_e32 v252, v76, v76
	v_add_f32_e32 v247, v247, v249
	v_mul_f32_e32 v249, v78, v78
	v_fmac_f32_e32 v252, v77, v77
	v_fmac_f32_e32 v249, v79, v79
	v_add_f32_e32 v252, v252, v249
	v_add_f32_e32 v247, v247, v252
	v_mov_b32_e32 v151, v247
	v_cvt_pk_bf16_f32 v116, v80, v81
	v_lshlrev_b32_e32 v218, 16, v116
	v_and_b32_e32 v219, 0xffff0000, v116
	v_pk_add_f32 v[80:81], v[80:81], v[218:219] neg_lo:[0,1] neg_hi:[0,1]
	s_nop 0
	v_cvt_pk_bf16_f32 v120, v80, v81
	v_cvt_pk_bf16_f32 v117, v82, v83
	v_lshlrev_b32_e32 v222, 16, v117
	v_and_b32_e32 v223, 0xffff0000, v117
	v_pk_add_f32 v[82:83], v[82:83], v[222:223] neg_lo:[0,1] neg_hi:[0,1]
	s_nop 0
	v_cvt_pk_bf16_f32 v121, v82, v83
	v_cvt_pk_bf16_f32 v118, v76, v77
	v_lshlrev_b32_e32 v218, 16, v118
	v_and_b32_e32 v219, 0xffff0000, v118
	v_pk_add_f32 v[76:77], v[76:77], v[218:219] neg_lo:[0,1] neg_hi:[0,1]
	s_nop 0
	v_cvt_pk_bf16_f32 v122, v76, v77
	v_cvt_pk_bf16_f32 v119, v78, v79
	v_lshlrev_b32_e32 v222, 16, v119
	v_and_b32_e32 v223, 0xffff0000, v119
	v_pk_add_f32 v[78:79], v[78:79], v[222:223] neg_lo:[0,1] neg_hi:[0,1]
	s_nop 0
	v_cvt_pk_bf16_f32 v123, v78, v79
	v_lshlrev_b32_e32 v218, 16, v124
	v_and_b32_e32 v219, 0xffff0000, v124
	v_lshlrev_b32_e32 v220, 16, v128
	v_and_b32_e32 v221, 0xffff0000, v128
	v_pk_add_f32 v[218:219], v[220:221], v[218:219]
	s_nop 0
	v_pk_fma_f32 v[72:73], s[20:21], v[72:73], v[218:219]
	v_lshlrev_b32_e32 v222, 16, v125
	v_and_b32_e32 v223, 0xffff0000, v125
	v_lshlrev_b32_e32 v250, 16, v129
	v_and_b32_e32 v251, 0xffff0000, v129
	v_pk_add_f32 v[222:223], v[250:251], v[222:223]
	s_nop 0
	v_pk_fma_f32 v[74:75], s[20:21], v[74:75], v[222:223]
	v_lshlrev_b32_e32 v218, 16, v126
	v_and_b32_e32 v219, 0xffff0000, v126
	v_lshlrev_b32_e32 v220, 16, v130
	v_and_b32_e32 v221, 0xffff0000, v130
	v_pk_add_f32 v[218:219], v[220:221], v[218:219]
	s_nop 0
	v_pk_fma_f32 v[68:69], s[20:21], v[68:69], v[218:219]
	v_lshlrev_b32_e32 v222, 16, v127
	v_and_b32_e32 v223, 0xffff0000, v127
	v_lshlrev_b32_e32 v250, 16, v131
	v_and_b32_e32 v251, 0xffff0000, v131
	v_pk_add_f32 v[222:223], v[250:251], v[222:223]
	s_nop 0
	v_pk_fma_f32 v[70:71], s[20:21], v[70:71], v[222:223]
	v_pk_add_f32 v[72:73], v[40:41], v[72:73]
	v_pk_add_f32 v[74:75], v[42:43], v[74:75]
	v_pk_add_f32 v[68:69], v[36:37], v[68:69]
	v_pk_add_f32 v[70:71], v[38:39], v[70:71]
	v_mul_f32_e32 v247, v72, v72
	v_mul_f32_e32 v249, v74, v74
	v_fmac_f32_e32 v247, v73, v73
	v_fmac_f32_e32 v249, v75, v75
	v_mul_f32_e32 v252, v68, v68
	v_add_f32_e32 v247, v247, v249
	v_mul_f32_e32 v249, v70, v70
	v_fmac_f32_e32 v252, v69, v69
	v_fmac_f32_e32 v249, v71, v71
	v_add_f32_e32 v252, v252, v249
	v_add_f32_e32 v247, v247, v252
	v_add_f32_e32 v151, v151, v247
	v_cvt_pk_bf16_f32 v124, v72, v73
	v_lshlrev_b32_e32 v218, 16, v124
	v_and_b32_e32 v219, 0xffff0000, v124
	v_pk_add_f32 v[72:73], v[72:73], v[218:219] neg_lo:[0,1] neg_hi:[0,1]
	s_nop 0
	v_cvt_pk_bf16_f32 v128, v72, v73
	v_cvt_pk_bf16_f32 v125, v74, v75
	v_lshlrev_b32_e32 v222, 16, v125
	v_and_b32_e32 v223, 0xffff0000, v125
	v_pk_add_f32 v[74:75], v[74:75], v[222:223] neg_lo:[0,1] neg_hi:[0,1]
	s_nop 0
	v_cvt_pk_bf16_f32 v129, v74, v75
	v_cvt_pk_bf16_f32 v126, v68, v69
	v_lshlrev_b32_e32 v218, 16, v126
	v_and_b32_e32 v219, 0xffff0000, v126
	v_pk_add_f32 v[68:69], v[68:69], v[218:219] neg_lo:[0,1] neg_hi:[0,1]
	s_nop 0
	v_cvt_pk_bf16_f32 v130, v68, v69
	v_cvt_pk_bf16_f32 v127, v70, v71
	v_lshlrev_b32_e32 v222, 16, v127
	v_and_b32_e32 v223, 0xffff0000, v127
	v_pk_add_f32 v[70:71], v[70:71], v[222:223] neg_lo:[0,1] neg_hi:[0,1]
	s_nop 0
	v_cvt_pk_bf16_f32 v131, v70, v71
	v_add_u32_e32 v245, 0x40000, v212
	global_store_dwordx4 v245, v[116:119], s[78:79]
	global_store_dwordx4 v245, v[120:123], s[28:29]
	global_store_dwordx4 v245, v[124:127], s[78:79] offset:64
	global_store_dwordx4 v245, v[128:131], s[28:29] offset:64
	s_waitcnt vmcnt(20)
;     __device__ __forceinline__ void operator()(const f32x4 (&acc)[2][2][4][2], const Unit& u, int wr, int wc, int fr, int fq) const {
;     ...
;             for (int m = 0; m < 2; ++m) { const int r = row0 + ai * HALF + (mh + m) * 16; float s = 0.f;
; #pragma unroll
;                 for (int bj = 0; bj < 2; ++bj) { const size_t c = (size_t)r * 1024 + col0 + bj * 32; const u32x4 h = rh[m][bj], l = rl[m][bj]; f32x4 b0, b1;
;                     if (xin) { b0 = __builtin_bit_cast(f32x4, h); b1 = __builtin_bit_cast(f32x4, l); }
;                     else { b0 = (f32x4){__uint_as_float(h.x << 16) + __uint_as_float(l.x << 16), __uint_as_float(h.x & 0xffff0000u) + __uint_as_float(l.x & 0xffff0000u),
;                                         __uint_as_float(h.y << 16) + __uint_as_float(l.y << 16), __uint_as_float(h.y & 0xffff0000u) + __uint_as_float(l.y & 0xffff0000u)};
;                            b1 = (f32x4){__uint_as_float(h.z << 16) + __uint_as_float(l.z << 16), __uint_as_float(h.z & 0xffff0000u) + __uint_as_float(l.z & 0xffff0000u),
;                                         __uint_as_float(h.w << 16) + __uint_as_float(l.w << 16), __uint_as_float(h.w & 0xffff0000u) + __uint_as_float(l.w & 0xffff0000u)}; }
;                     const f32x4 v0 = b0 + acc[ai][bj][mh + m][0] * scale + bv[bj][0], v1 = b1 + acc[ai][bj][mh + m][1] * scale + bv[bj][1];
;                     if (fout) { *(f32x4*)(fout + c) = v0; *(f32x4*)(fout + c + 4) = v1; }
;                     else { const unsigned h0 = pk2(v0[0], v0[1]), h1 = pk2(v0[2], v0[3]), h2 = pk2(v1[0], v1[1]), h3 = pk2(v1[2], v1[3]);
;                         const unsigned l0 = pk2(v0[0] - __uint_as_float(h0 << 16), v0[1] - __uint_as_float(h0 & 0xffff0000u)), l1 = pk2(v0[2] - __uint_as_float(h1 << 16), v0[3] - __uint_as_float(h1 & 0xffff0000u)),
;                                        l2 = pk2(v1[0] - __uint_as_float(h2 << 16), v1[1] - __uint_as_float(h2 & 0xffff0000u)), l3 = pk2(v1[2] - __uint_as_float(h3 << 16), v1[3] - __uint_as_float(h3 & 0xffff0000u));
;                         *(u32x4*)(hi + c) = (u32x4){h0, h1, h2, h3}; *(u32x4*)(lo_out + c) = (u32x4){l0, l1, l2, l3}; }
;                     s += ((v0[0] * v0[0] + v0[1] * v0[1]) + (v0[2] * v0[2] + v0[3] * v0[3])) + ((v1[0] * v1[0] + v1[1] * v1[1]) + (v1[2] * v1[2] + v1[3] * v1[3])); }
	v_lshlrev_b32_e32 v218, 16, v164
	v_and_b32_e32 v219, 0xffff0000, v164
	v_lshlrev_b32_e32 v220, 16, v168
	v_and_b32_e32 v221, 0xffff0000, v168
	v_pk_add_f32 v[218:219], v[220:221], v[218:219]
	s_nop 0
	v_pk_fma_f32 v[64:65], s[20:21], v[64:65], v[218:219]
	v_lshlrev_b32_e32 v222, 16, v165
	v_and_b32_e32 v223, 0xffff0000, v165
	v_lshlrev_b32_e32 v250, 16, v169
	v_and_b32_e32 v251, 0xffff0000, v169
	v_pk_add_f32 v[222:223], v[250:251], v[222:223]
	s_nop 0
	v_pk_fma_f32 v[66:67], s[20:21], v[66:67], v[222:223]
	v_lshlrev_b32_e32 v218, 16, v166
	v_and_b32_e32 v219, 0xffff0000, v166
	v_lshlrev_b32_e32 v220, 16, v170
	v_and_b32_e32 v221, 0xffff0000, v170
	v_pk_add_f32 v[218:219], v[220:221], v[218:219]
	s_nop 0
	v_pk_fma_f32 v[60:61], s[20:21], v[60:61], v[218:219]
	v_lshlrev_b32_e32 v222, 16, v167
	v_and_b32_e32 v223, 0xffff0000, v167
	v_lshlrev_b32_e32 v250, 16, v171
	v_and_b32_e32 v251, 0xffff0000, v171
	v_pk_add_f32 v[222:223], v[250:251], v[222:223]
	s_nop 0
	v_pk_fma_f32 v[62:63], s[20:21], v[62:63], v[222:223]
	v_pk_add_f32 v[64:65], v[56:57], v[64:65]
	v_pk_add_f32 v[66:67], v[58:59], v[66:67]
	v_pk_add_f32 v[60:61], v[48:49], v[60:61]
	v_pk_add_f32 v[62:63], v[50:51], v[62:63]
	v_mul_f32_e32 v247, v64, v64
	v_mul_f32_e32 v249, v66, v66
	v_fmac_f32_e32 v247, v65, v65
	v_fmac_f32_e32 v249, v67, v67
	v_mul_f32_e32 v252, v60, v60
	v_add_f32_e32 v247, v247, v249
	v_mul_f32_e32 v249, v62, v62
	v_fmac_f32_e32 v252, v61, v61
	v_fmac_f32_e32 v249, v63, v63
	v_add_f32_e32 v252, v252, v249
	v_add_f32_e32 v247, v247, v252
	v_mov_b32_e32 v152, v247
	v_cvt_pk_bf16_f32 v164, v64, v65
	v_lshlrev_b32_e32 v218, 16, v164
	v_and_b32_e32 v219, 0xffff0000, v164
	v_pk_add_f32 v[64:65], v[64:65], v[218:219] neg_lo:[0,1] neg_hi:[0,1]
	s_nop 0
	v_cvt_pk_bf16_f32 v168, v64, v65
	v_cvt_pk_bf16_f32 v165, v66, v67
	v_lshlrev_b32_e32 v222, 16, v165
	v_and_b32_e32 v223, 0xffff0000, v165
	v_pk_add_f32 v[66:67], v[66:67], v[222:223] neg_lo:[0,1] neg_hi:[0,1]
	s_nop 0
	v_cvt_pk_bf16_f32 v169, v66, v67
	v_cvt_pk_bf16_f32 v166, v60, v61
	v_lshlrev_b32_e32 v218, 16, v166
	v_and_b32_e32 v219, 0xffff0000, v166
	v_pk_add_f32 v[60:61], v[60:61], v[218:219] neg_lo:[0,1] neg_hi:[0,1]
	s_nop 0
	v_cvt_pk_bf16_f32 v170, v60, v61
	v_cvt_pk_bf16_f32 v167, v62, v63
	v_lshlrev_b32_e32 v222, 16, v167
	v_and_b32_e32 v223, 0xffff0000, v167
	v_pk_add_f32 v[62:63], v[62:63], v[222:223] neg_lo:[0,1] neg_hi:[0,1]
	s_nop 0
	v_cvt_pk_bf16_f32 v171, v62, v63
	v_lshlrev_b32_e32 v218, 16, v172
	v_and_b32_e32 v219, 0xffff0000, v172
	v_lshlrev_b32_e32 v220, 16, v176
	v_and_b32_e32 v221, 0xffff0000, v176
	v_pk_add_f32 v[218:219], v[220:221], v[218:219]
	s_nop 0
	v_pk_fma_f32 v[52:53], s[20:21], v[52:53], v[218:219]
	v_lshlrev_b32_e32 v222, 16, v173
	v_and_b32_e32 v223, 0xffff0000, v173
	v_lshlrev_b32_e32 v250, 16, v177
	v_and_b32_e32 v251, 0xffff0000, v177
	v_pk_add_f32 v[222:223], v[250:251], v[222:223]
	s_nop 0
	v_pk_fma_f32 v[54:55], s[20:21], v[54:55], v[222:223]
	v_lshlrev_b32_e32 v218, 16, v174
	v_and_b32_e32 v219, 0xffff0000, v174
	v_lshlrev_b32_e32 v220, 16, v178
	v_and_b32_e32 v221, 0xffff0000, v178
	v_pk_add_f32 v[218:219], v[220:221], v[218:219]
	s_nop 0
	v_pk_fma_f32 v[44:45], s[20:21], v[44:45], v[218:219]
	v_lshlrev_b32_e32 v222, 16, v175
	v_and_b32_e32 v223, 0xffff0000, v175
	v_lshlrev_b32_e32 v250, 16, v179
	v_and_b32_e32 v251, 0xffff0000, v179
	v_pk_add_f32 v[222:223], v[250:251], v[222:223]
	s_nop 0
	v_pk_fma_f32 v[46:47], s[20:21], v[46:47], v[222:223]
	v_pk_add_f32 v[52:53], v[40:41], v[52:53]
	v_pk_add_f32 v[54:55], v[42:43], v[54:55]
	v_pk_add_f32 v[44:45], v[36:37], v[44:45]
	v_pk_add_f32 v[46:47], v[38:39], v[46:47]
	v_mul_f32_e32 v247, v52, v52
	v_mul_f32_e32 v249, v54, v54
	v_fmac_f32_e32 v247, v53, v53
	v_fmac_f32_e32 v249, v55, v55
	v_mul_f32_e32 v252, v44, v44
	v_add_f32_e32 v247, v247, v249
	v_mul_f32_e32 v249, v46, v46
	v_fmac_f32_e32 v252, v45, v45
	v_fmac_f32_e32 v249, v47, v47
	v_add_f32_e32 v252, v252, v249
	v_add_f32_e32 v247, v247, v252
	v_add_f32_e32 v152, v152, v247
	v_cvt_pk_bf16_f32 v172, v52, v53
	v_lshlrev_b32_e32 v218, 16, v172
	v_and_b32_e32 v219, 0xffff0000, v172
	v_pk_add_f32 v[52:53], v[52:53], v[218:219] neg_lo:[0,1] neg_hi:[0,1]
	s_nop 0
	v_cvt_pk_bf16_f32 v176, v52, v53
	v_cvt_pk_bf16_f32 v173, v54, v55
	v_lshlrev_b32_e32 v222, 16, v173
	v_and_b32_e32 v223, 0xffff0000, v173
	v_pk_add_f32 v[54:55], v[54:55], v[222:223] neg_lo:[0,1] neg_hi:[0,1]
	s_nop 0
	v_cvt_pk_bf16_f32 v177, v54, v55
	v_cvt_pk_bf16_f32 v174, v44, v45
	v_lshlrev_b32_e32 v218, 16, v174
	v_and_b32_e32 v219, 0xffff0000, v174
	v_pk_add_f32 v[44:45], v[44:45], v[218:219] neg_lo:[0,1] neg_hi:[0,1]
	s_nop 0
	v_cvt_pk_bf16_f32 v178, v44, v45
	v_cvt_pk_bf16_f32 v175, v46, v47
	v_lshlrev_b32_e32 v222, 16, v175
	v_and_b32_e32 v223, 0xffff0000, v175
	v_pk_add_f32 v[46:47], v[46:47], v[222:223] neg_lo:[0,1] neg_hi:[0,1]
	s_nop 0
	v_cvt_pk_bf16_f32 v179, v46, v47
	v_add_u32_e32 v245, 0x48000, v212
	global_store_dwordx4 v245, v[164:167], s[78:79]
	global_store_dwordx4 v245, v[168:171], s[28:29]
	global_store_dwordx4 v245, v[172:175], s[78:79] offset:64
	global_store_dwordx4 v245, v[176:179], s[28:29] offset:64
	s_waitcnt vmcnt(20)
;     __device__ __forceinline__ void operator()(const f32x4 (&acc)[2][2][4][2], const Unit& u, int wr, int wc, int fr, int fq) const {
;     ...
;             for (int m = 0; m < 2; ++m) { const int r = row0 + ai * HALF + (mh + m) * 16; float s = 0.f;
; #pragma unroll
;                 for (int bj = 0; bj < 2; ++bj) { const size_t c = (size_t)r * 1024 + col0 + bj * 32; const u32x4 h = rh[m][bj], l = rl[m][bj]; f32x4 b0, b1;
;                     if (xin) { b0 = __builtin_bit_cast(f32x4, h); b1 = __builtin_bit_cast(f32x4, l); }
;                     else { b0 = (f32x4){__uint_as_float(h.x << 16) + __uint_as_float(l.x << 16), __uint_as_float(h.x & 0xffff0000u) + __uint_as_float(l.x & 0xffff0000u),
;                                         __uint_as_float(h.y << 16) + __uint_as_float(l.y << 16), __uint_as_float(h.y & 0xffff0000u) + __uint_as_float(l.y & 0xffff0000u)};
;                            b1 = (f32x4){__uint_as_float(h.z << 16) + __uint_as_float(l.z << 16), __uint_as_float(h.z & 0xffff0000u) + __uint_as_float(l.z & 0xffff0000u),
;                                         __uint_as_float(h.w << 16) + __uint_as_float(l.w << 16), __uint_as_float(h.w & 0xffff0000u) + __uint_as_float(l.w & 0xffff0000u)}; }
;                     const f32x4 v0 = b0 + acc[ai][bj][mh + m][0] * scale + bv[bj][0], v1 = b1 + acc[ai][bj][mh + m][1] * scale + bv[bj][1];
;                     if (fout) { *(f32x4*)(fout + c) = v0; *(f32x4*)(fout + c + 4) = v1; }
;                     else { const unsigned h0 = pk2(v0[0], v0[1]), h1 = pk2(v0[2], v0[3]), h2 = pk2(v1[0], v1[1]), h3 = pk2(v1[2], v1[3]);
;                         const unsigned l0 = pk2(v0[0] - __uint_as_float(h0 << 16), v0[1] - __uint_as_float(h0 & 0xffff0000u)), l1 = pk2(v0[2] - __uint_as_float(h1 << 16), v0[3] - __uint_as_float(h1 & 0xffff0000u)),
;                                        l2 = pk2(v1[0] - __uint_as_float(h2 << 16), v1[1] - __uint_as_float(h2 & 0xffff0000u)), l3 = pk2(v1[2] - __uint_as_float(h3 << 16), v1[3] - __uint_as_float(h3 & 0xffff0000u));
;                         *(u32x4*)(hi + c) = (u32x4){h0, h1, h2, h3}; *(u32x4*)(lo_out + c) = (u32x4){l0, l1, l2, l3}; }
;                     s += ((v0[0] * v0[0] + v0[1] * v0[1]) + (v0[2] * v0[2] + v0[3] * v0[3])) + ((v1[0] * v1[0] + v1[1] * v1[1]) + (v1[2] * v1[2] + v1[3] * v1[3])); }
	v_lshlrev_b32_e32 v218, 16, v100
	v_and_b32_e32 v219, 0xffff0000, v100
	v_lshlrev_b32_e32 v220, 16, v104
	v_and_b32_e32 v221, 0xffff0000, v104
	v_pk_add_f32 v[218:219], v[220:221], v[218:219]
	s_nop 0
	v_pk_fma_f32 v[32:33], s[20:21], v[32:33], v[218:219]
	v_lshlrev_b32_e32 v222, 16, v101
	v_and_b32_e32 v223, 0xffff0000, v101
	v_lshlrev_b32_e32 v250, 16, v105
	v_and_b32_e32 v251, 0xffff0000, v105
	v_pk_add_f32 v[222:223], v[250:251], v[222:223]
	s_nop 0
	v_pk_fma_f32 v[34:35], s[20:21], v[34:35], v[222:223]
	v_lshlrev_b32_e32 v218, 16, v102
	v_and_b32_e32 v219, 0xffff0000, v102
	v_lshlrev_b32_e32 v220, 16, v106
	v_and_b32_e32 v221, 0xffff0000, v106
	v_pk_add_f32 v[218:219], v[220:221], v[218:219]
	s_nop 0
	v_pk_fma_f32 v[28:29], s[20:21], v[28:29], v[218:219]
	v_lshlrev_b32_e32 v222, 16, v103
	v_and_b32_e32 v223, 0xffff0000, v103
	v_lshlrev_b32_e32 v250, 16, v107
	v_and_b32_e32 v251, 0xffff0000, v107
	v_pk_add_f32 v[222:223], v[250:251], v[222:223]
	s_nop 0
	v_pk_fma_f32 v[30:31], s[20:21], v[30:31], v[222:223]
	v_pk_add_f32 v[32:33], v[56:57], v[32:33]
	v_pk_add_f32 v[34:35], v[58:59], v[34:35]
	v_pk_add_f32 v[28:29], v[48:49], v[28:29]
	v_pk_add_f32 v[30:31], v[50:51], v[30:31]
	v_mul_f32_e32 v247, v32, v32
	v_mul_f32_e32 v249, v34, v34
	v_fmac_f32_e32 v247, v33, v33
	v_fmac_f32_e32 v249, v35, v35
	v_mul_f32_e32 v252, v28, v28
	v_add_f32_e32 v247, v247, v249
	v_mul_f32_e32 v249, v30, v30
	v_fmac_f32_e32 v252, v29, v29
	v_fmac_f32_e32 v249, v31, v31
	v_add_f32_e32 v252, v252, v249
	v_add_f32_e32 v247, v247, v252
	v_mov_b32_e32 v153, v247
	v_cvt_pk_bf16_f32 v100, v32, v33
	v_lshlrev_b32_e32 v218, 16, v100
	v_and_b32_e32 v219, 0xffff0000, v100
	v_pk_add_f32 v[32:33], v[32:33], v[218:219] neg_lo:[0,1] neg_hi:[0,1]
	s_nop 0
	v_cvt_pk_bf16_f32 v104, v32, v33
	v_cvt_pk_bf16_f32 v101, v34, v35
	v_lshlrev_b32_e32 v222, 16, v101
	v_and_b32_e32 v223, 0xffff0000, v101
	v_pk_add_f32 v[34:35], v[34:35], v[222:223] neg_lo:[0,1] neg_hi:[0,1]
	s_nop 0
	v_cvt_pk_bf16_f32 v105, v34, v35
	v_cvt_pk_bf16_f32 v102, v28, v29
	v_lshlrev_b32_e32 v218, 16, v102
	v_and_b32_e32 v219, 0xffff0000, v102
	v_pk_add_f32 v[28:29], v[28:29], v[218:219] neg_lo:[0,1] neg_hi:[0,1]
	s_nop 0
	v_cvt_pk_bf16_f32 v106, v28, v29
	v_cvt_pk_bf16_f32 v103, v30, v31
	v_lshlrev_b32_e32 v222, 16, v103
	v_and_b32_e32 v223, 0xffff0000, v103
	v_pk_add_f32 v[30:31], v[30:31], v[222:223] neg_lo:[0,1] neg_hi:[0,1]
	s_nop 0
	v_cvt_pk_bf16_f32 v107, v30, v31
	v_lshlrev_b32_e32 v218, 16, v108
	v_and_b32_e32 v219, 0xffff0000, v108
	v_lshlrev_b32_e32 v220, 16, v112
	v_and_b32_e32 v221, 0xffff0000, v112
	v_pk_add_f32 v[218:219], v[220:221], v[218:219]
	s_nop 0
	v_pk_fma_f32 v[24:25], s[20:21], v[24:25], v[218:219]
	v_lshlrev_b32_e32 v222, 16, v109
	v_and_b32_e32 v223, 0xffff0000, v109
	v_lshlrev_b32_e32 v250, 16, v113
	v_and_b32_e32 v251, 0xffff0000, v113
	v_pk_add_f32 v[222:223], v[250:251], v[222:223]
	s_nop 0
	v_pk_fma_f32 v[26:27], s[20:21], v[26:27], v[222:223]
	v_lshlrev_b32_e32 v218, 16, v110
	v_and_b32_e32 v219, 0xffff0000, v110
	v_lshlrev_b32_e32 v220, 16, v114
	v_and_b32_e32 v221, 0xffff0000, v114
	v_pk_add_f32 v[218:219], v[220:221], v[218:219]
	s_nop 0
	v_pk_fma_f32 v[20:21], s[20:21], v[20:21], v[218:219]
	v_lshlrev_b32_e32 v222, 16, v111
	v_and_b32_e32 v223, 0xffff0000, v111
	v_lshlrev_b32_e32 v250, 16, v115
	v_and_b32_e32 v251, 0xffff0000, v115
	v_pk_add_f32 v[222:223], v[250:251], v[222:223]
	s_nop 0
	v_pk_fma_f32 v[22:23], s[20:21], v[22:23], v[222:223]
	v_pk_add_f32 v[24:25], v[40:41], v[24:25]
	v_pk_add_f32 v[26:27], v[42:43], v[26:27]
	v_pk_add_f32 v[20:21], v[36:37], v[20:21]
	v_pk_add_f32 v[22:23], v[38:39], v[22:23]
	v_mul_f32_e32 v247, v24, v24
	v_mul_f32_e32 v249, v26, v26
	v_fmac_f32_e32 v247, v25, v25
	v_fmac_f32_e32 v249, v27, v27
	v_mul_f32_e32 v252, v20, v20
	v_add_f32_e32 v247, v247, v249
	v_mul_f32_e32 v249, v22, v22
	v_fmac_f32_e32 v252, v21, v21
	v_fmac_f32_e32 v249, v23, v23
	v_add_f32_e32 v252, v252, v249
	v_add_f32_e32 v247, v247, v252
	v_add_f32_e32 v153, v153, v247
	v_cvt_pk_bf16_f32 v108, v24, v25
	v_lshlrev_b32_e32 v218, 16, v108
	v_and_b32_e32 v219, 0xffff0000, v108
	v_pk_add_f32 v[24:25], v[24:25], v[218:219] neg_lo:[0,1] neg_hi:[0,1]
	s_nop 0
	v_cvt_pk_bf16_f32 v112, v24, v25
	v_cvt_pk_bf16_f32 v109, v26, v27
	v_lshlrev_b32_e32 v222, 16, v109
	v_and_b32_e32 v223, 0xffff0000, v109
	v_pk_add_f32 v[26:27], v[26:27], v[222:223] neg_lo:[0,1] neg_hi:[0,1]
	s_nop 0
	v_cvt_pk_bf16_f32 v113, v26, v27
	v_cvt_pk_bf16_f32 v110, v20, v21
	v_lshlrev_b32_e32 v218, 16, v110
	v_and_b32_e32 v219, 0xffff0000, v110
	v_pk_add_f32 v[20:21], v[20:21], v[218:219] neg_lo:[0,1] neg_hi:[0,1]
	s_nop 0
	v_cvt_pk_bf16_f32 v114, v20, v21
	v_cvt_pk_bf16_f32 v111, v22, v23
	v_lshlrev_b32_e32 v222, 16, v111
	v_and_b32_e32 v223, 0xffff0000, v111
	v_pk_add_f32 v[22:23], v[22:23], v[222:223] neg_lo:[0,1] neg_hi:[0,1]
	s_nop 0
	v_cvt_pk_bf16_f32 v115, v22, v23
	v_add_u32_e32 v245, 0x50000, v212
	global_store_dwordx4 v245, v[100:103], s[78:79]
	global_store_dwordx4 v245, v[104:107], s[28:29]
	global_store_dwordx4 v245, v[108:111], s[78:79] offset:64
	global_store_dwordx4 v245, v[112:115], s[28:29] offset:64
	s_waitcnt vmcnt(16)
;     __device__ __forceinline__ void operator()(const f32x4 (&acc)[2][2][4][2], const Unit& u, int wr, int wc, int fr, int fq) const {
;     ...
;             for (int m = 0; m < 2; ++m) { const int r = row0 + ai * HALF + (mh + m) * 16; float s = 0.f;
; #pragma unroll
;                 for (int bj = 0; bj < 2; ++bj) { const size_t c = (size_t)r * 1024 + col0 + bj * 32; const u32x4 h = rh[m][bj], l = rl[m][bj]; f32x4 b0, b1;
;                     if (xin) { b0 = __builtin_bit_cast(f32x4, h); b1 = __builtin_bit_cast(f32x4, l); }
;                     else { b0 = (f32x4){__uint_as_float(h.x << 16) + __uint_as_float(l.x << 16), __uint_as_float(h.x & 0xffff0000u) + __uint_as_float(l.x & 0xffff0000u),
;                                         __uint_as_float(h.y << 16) + __uint_as_float(l.y << 16), __uint_as_float(h.y & 0xffff0000u) + __uint_as_float(l.y & 0xffff0000u)};
;                            b1 = (f32x4){__uint_as_float(h.z << 16) + __uint_as_float(l.z << 16), __uint_as_float(h.z & 0xffff0000u) + __uint_as_float(l.z & 0xffff0000u),
;                                         __uint_as_float(h.w << 16) + __uint_as_float(l.w << 16), __uint_as_float(h.w & 0xffff0000u) + __uint_as_float(l.w & 0xffff0000u)}; }
;                     const f32x4 v0 = b0 + acc[ai][bj][mh + m][0] * scale + bv[bj][0], v1 = b1 + acc[ai][bj][mh + m][1] * scale + bv[bj][1];
;                     if (fout) { *(f32x4*)(fout + c) = v0; *(f32x4*)(fout + c + 4) = v1; }
;                     else { const unsigned h0 = pk2(v0[0], v0[1]), h1 = pk2(v0[2], v0[3]), h2 = pk2(v1[0], v1[1]), h3 = pk2(v1[2], v1[3]);
;                         const unsigned l0 = pk2(v0[0] - __uint_as_float(h0 << 16), v0[1] - __uint_as_float(h0 & 0xffff0000u)), l1 = pk2(v0[2] - __uint_as_float(h1 << 16), v0[3] - __uint_as_float(h1 & 0xffff0000u)),
;                                        l2 = pk2(v1[0] - __uint_as_float(h2 << 16), v1[1] - __uint_as_float(h2 & 0xffff0000u)), l3 = pk2(v1[2] - __uint_as_float(h3 << 16), v1[3] - __uint_as_float(h3 & 0xffff0000u));
;                         *(u32x4*)(hi + c) = (u32x4){h0, h1, h2, h3}; *(u32x4*)(lo_out + c) = (u32x4){l0, l1, l2, l3}; }
;                     s += ((v0[0] * v0[0] + v0[1] * v0[1]) + (v0[2] * v0[2] + v0[3] * v0[3])) + ((v1[0] * v1[0] + v1[1] * v1[1]) + (v1[2] * v1[2] + v1[3] * v1[3])); }
;                 s += __shfl_xor(s, 16); s += __shfl_xor(s, 32);
	v_lshlrev_b32_e32 v218, 16, v196
	v_and_b32_e32 v219, 0xffff0000, v196
	v_lshlrev_b32_e32 v220, 16, v200
	v_and_b32_e32 v221, 0xffff0000, v200
	v_pk_add_f32 v[218:219], v[220:221], v[218:219]
	s_nop 0
	v_pk_fma_f32 v[16:17], s[20:21], v[16:17], v[218:219]
	v_lshlrev_b32_e32 v222, 16, v197
	v_and_b32_e32 v223, 0xffff0000, v197
	v_lshlrev_b32_e32 v250, 16, v201
	v_and_b32_e32 v251, 0xffff0000, v201
	v_pk_add_f32 v[222:223], v[250:251], v[222:223]
	s_nop 0
	v_pk_fma_f32 v[18:19], s[20:21], v[18:19], v[222:223]
	v_lshlrev_b32_e32 v218, 16, v198
	v_and_b32_e32 v219, 0xffff0000, v198
	v_lshlrev_b32_e32 v220, 16, v202
	v_and_b32_e32 v221, 0xffff0000, v202
	v_pk_add_f32 v[218:219], v[220:221], v[218:219]
	s_nop 0
	v_pk_fma_f32 v[12:13], s[20:21], v[12:13], v[218:219]
	v_lshlrev_b32_e32 v222, 16, v199
	v_and_b32_e32 v223, 0xffff0000, v199
	v_lshlrev_b32_e32 v250, 16, v203
	v_and_b32_e32 v251, 0xffff0000, v203
	v_pk_add_f32 v[222:223], v[250:251], v[222:223]
	s_nop 0
	v_pk_fma_f32 v[14:15], s[20:21], v[14:15], v[222:223]
	v_pk_add_f32 v[16:17], v[56:57], v[16:17]
	v_pk_add_f32 v[18:19], v[58:59], v[18:19]
	v_pk_add_f32 v[12:13], v[48:49], v[12:13]
	v_pk_add_f32 v[14:15], v[50:51], v[14:15]
	v_mul_f32_e32 v247, v16, v16
	v_mul_f32_e32 v249, v18, v18
	v_fmac_f32_e32 v247, v17, v17
	v_fmac_f32_e32 v249, v19, v19
	v_mul_f32_e32 v252, v12, v12
	v_add_f32_e32 v247, v247, v249
	v_mul_f32_e32 v249, v14, v14
	v_fmac_f32_e32 v252, v13, v13
	v_fmac_f32_e32 v249, v15, v15
	v_add_f32_e32 v252, v252, v249
	v_add_f32_e32 v247, v247, v252
	v_mov_b32_e32 v154, v247
	v_cvt_pk_bf16_f32 v196, v16, v17
	v_lshlrev_b32_e32 v218, 16, v196
	v_and_b32_e32 v219, 0xffff0000, v196
	v_pk_add_f32 v[16:17], v[16:17], v[218:219] neg_lo:[0,1] neg_hi:[0,1]
	s_nop 0
	v_cvt_pk_bf16_f32 v200, v16, v17
	v_cvt_pk_bf16_f32 v197, v18, v19
	v_lshlrev_b32_e32 v222, 16, v197
	v_and_b32_e32 v223, 0xffff0000, v197
	v_pk_add_f32 v[18:19], v[18:19], v[222:223] neg_lo:[0,1] neg_hi:[0,1]
	s_nop 0
	v_cvt_pk_bf16_f32 v201, v18, v19
	v_cvt_pk_bf16_f32 v198, v12, v13
	v_lshlrev_b32_e32 v218, 16, v198
	v_and_b32_e32 v219, 0xffff0000, v198
	v_pk_add_f32 v[12:13], v[12:13], v[218:219] neg_lo:[0,1] neg_hi:[0,1]
	s_nop 0
	v_cvt_pk_bf16_f32 v202, v12, v13
	v_cvt_pk_bf16_f32 v199, v14, v15
	v_lshlrev_b32_e32 v222, 16, v199
	v_and_b32_e32 v223, 0xffff0000, v199
	v_pk_add_f32 v[14:15], v[14:15], v[222:223] neg_lo:[0,1] neg_hi:[0,1]
	s_nop 0
	v_cvt_pk_bf16_f32 v203, v14, v15
	v_lshlrev_b32_e32 v218, 16, v204
	v_and_b32_e32 v219, 0xffff0000, v204
	v_lshlrev_b32_e32 v220, 16, v208
	v_and_b32_e32 v221, 0xffff0000, v208
	v_pk_add_f32 v[218:219], v[220:221], v[218:219]
	s_nop 0
	v_pk_fma_f32 v[8:9], s[20:21], v[8:9], v[218:219]
	v_lshlrev_b32_e32 v222, 16, v205
	v_and_b32_e32 v223, 0xffff0000, v205
	v_lshlrev_b32_e32 v250, 16, v209
	v_and_b32_e32 v251, 0xffff0000, v209
	v_pk_add_f32 v[222:223], v[250:251], v[222:223]
	s_nop 0
	v_pk_fma_f32 v[10:11], s[20:21], v[10:11], v[222:223]
	v_lshlrev_b32_e32 v218, 16, v206
	v_and_b32_e32 v219, 0xffff0000, v206
	v_lshlrev_b32_e32 v220, 16, v210
	v_and_b32_e32 v221, 0xffff0000, v210
	v_pk_add_f32 v[218:219], v[220:221], v[218:219]
	s_nop 0
	v_pk_fma_f32 v[4:5], s[20:21], v[4:5], v[218:219]
	v_lshlrev_b32_e32 v222, 16, v207
	v_and_b32_e32 v223, 0xffff0000, v207
	v_lshlrev_b32_e32 v250, 16, v211
	v_and_b32_e32 v251, 0xffff0000, v211
	v_pk_add_f32 v[222:223], v[250:251], v[222:223]
	s_nop 0
	v_pk_fma_f32 v[6:7], s[20:21], v[6:7], v[222:223]
	v_pk_add_f32 v[8:9], v[40:41], v[8:9]
	v_pk_add_f32 v[10:11], v[42:43], v[10:11]
	v_pk_add_f32 v[4:5], v[36:37], v[4:5]
	v_pk_add_f32 v[6:7], v[38:39], v[6:7]
	v_mul_f32_e32 v247, v8, v8
	v_mul_f32_e32 v249, v10, v10
	v_fmac_f32_e32 v247, v9, v9
	v_fmac_f32_e32 v249, v11, v11
	v_mul_f32_e32 v252, v4, v4
	v_add_f32_e32 v247, v247, v249
	v_mul_f32_e32 v249, v6, v6
	v_fmac_f32_e32 v252, v5, v5
	v_fmac_f32_e32 v249, v7, v7
	v_add_f32_e32 v252, v252, v249
	v_add_f32_e32 v247, v247, v252
	v_add_f32_e32 v154, v154, v247
	v_cvt_pk_bf16_f32 v204, v8, v9
	v_lshlrev_b32_e32 v218, 16, v204
	v_and_b32_e32 v219, 0xffff0000, v204
	v_pk_add_f32 v[8:9], v[8:9], v[218:219] neg_lo:[0,1] neg_hi:[0,1]
	s_nop 0
	v_cvt_pk_bf16_f32 v208, v8, v9
	v_cvt_pk_bf16_f32 v205, v10, v11
	v_lshlrev_b32_e32 v222, 16, v205
	v_and_b32_e32 v223, 0xffff0000, v205
	v_pk_add_f32 v[10:11], v[10:11], v[222:223] neg_lo:[0,1] neg_hi:[0,1]
	s_nop 0
	v_cvt_pk_bf16_f32 v209, v10, v11
	v_cvt_pk_bf16_f32 v206, v4, v5
	v_lshlrev_b32_e32 v218, 16, v206
	v_and_b32_e32 v219, 0xffff0000, v206
	v_pk_add_f32 v[4:5], v[4:5], v[218:219] neg_lo:[0,1] neg_hi:[0,1]
	s_nop 0
	v_cvt_pk_bf16_f32 v210, v4, v5
	v_cvt_pk_bf16_f32 v207, v6, v7
	v_lshlrev_b32_e32 v222, 16, v207
	v_and_b32_e32 v223, 0xffff0000, v207
	v_pk_add_f32 v[6:7], v[6:7], v[222:223] neg_lo:[0,1] neg_hi:[0,1]
	s_nop 0
	v_cvt_pk_bf16_f32 v211, v6, v7
	v_add_u32_e32 v245, 0x58000, v212
	global_store_dwordx4 v245, v[196:199], s[78:79]
	global_store_dwordx4 v245, v[200:203], s[28:29]
	global_store_dwordx4 v245, v[204:207], s[78:79] offset:64
	global_store_dwordx4 v245, v[208:211], s[28:29] offset:64
	v_xor_b32_e32 v155, 16, v236
	v_xor_b32_e32 v156, 32, v236
	v_lshlrev_b32_e32 v155, 2, v155
	v_lshlrev_b32_e32 v156, 2, v156
	ds_bpermute_b32 v157, v155, v213
	ds_bpermute_b32 v158, v155, v148
	ds_bpermute_b32 v159, v155, v149
	ds_bpermute_b32 v160, v155, v150
	ds_bpermute_b32 v161, v155, v151
	ds_bpermute_b32 v162, v155, v152
	ds_bpermute_b32 v163, v155, v153
	ds_bpermute_b32 v164, v155, v154
	s_waitcnt lgkmcnt(7)
;     __device__ __forceinline__ void operator()(const f32x4 (&acc)[2][2][4][2], const Unit& u, int wr, int wc, int fr, int fq) const {
;     ...
;                 s += __shfl_xor(s, 16); s += __shfl_xor(s, 32);
;                 if (fq == 0) ssn[(size_t)r * 16 + u.pn * 4 + wc] = s; }
	v_add_f32_e32 v213, v213, v157
	ds_bpermute_b32 v157, v156, v213
	s_waitcnt lgkmcnt(7)
	v_add_f32_e32 v148, v148, v158
	ds_bpermute_b32 v158, v156, v148
	s_waitcnt lgkmcnt(7)
	v_add_f32_e32 v149, v149, v159
	ds_bpermute_b32 v159, v156, v149
	s_waitcnt lgkmcnt(7)
	v_add_f32_e32 v150, v150, v160
	ds_bpermute_b32 v160, v156, v150
	s_waitcnt lgkmcnt(7)
	v_add_f32_e32 v151, v151, v161
	ds_bpermute_b32 v161, v156, v151
	s_waitcnt lgkmcnt(7)
	v_add_f32_e32 v152, v152, v162
	ds_bpermute_b32 v162, v156, v152
	s_waitcnt lgkmcnt(7)
	v_add_f32_e32 v153, v153, v163
	ds_bpermute_b32 v163, v156, v153
	s_waitcnt lgkmcnt(7)
	v_add_f32_e32 v154, v154, v164
	ds_bpermute_b32 v164, v156, v154
	s_lshl_b32 s46, s80, 4
	s_lshl_b32 s47, s72, 2
	s_add_u32 s46, s46, s47
	v_lshl_add_u32 v245, s81, 8, v187
	v_lshlrev_b32_e32 v245, 6, v245
	v_add_u32_e32 v245, s46, v245
	s_waitcnt lgkmcnt(7)
	v_add_f32_e32 v213, v213, v157
	s_waitcnt lgkmcnt(6)
	v_add_f32_e32 v148, v148, v158
	s_waitcnt lgkmcnt(5)
	v_add_f32_e32 v149, v149, v159
	s_waitcnt lgkmcnt(4)
	v_add_f32_e32 v150, v150, v160
	s_waitcnt lgkmcnt(3)
	v_add_f32_e32 v151, v151, v161
	s_waitcnt lgkmcnt(2)
	v_add_f32_e32 v152, v152, v162
	s_waitcnt lgkmcnt(1)
	v_add_f32_e32 v153, v153, v163
	s_waitcnt lgkmcnt(0)
	v_add_f32_e32 v154, v154, v164
	s_and_saveexec_b64 s[2:3], s[6:7]
	v_add_u32_e32 v217, 0x0, v245
	global_store_dword v217, v213, s[4:5]
	v_add_u32_e32 v217, 0x400, v245
	global_store_dword v217, v148, s[4:5]
	v_add_u32_e32 v217, 0x800, v245
	global_store_dword v217, v149, s[4:5]
	v_add_u32_e32 v217, 0xc00, v245
	global_store_dword v217, v150, s[4:5]
	v_add_u32_e32 v217, 0x2000, v245
	global_store_dword v217, v151, s[4:5]
	v_add_u32_e32 v217, 0x2400, v245
	global_store_dword v217, v152, s[4:5]
	v_add_u32_e32 v217, 0x2800, v245
	global_store_dword v217, v153, s[4:5]
	v_add_u32_e32 v217, 0x2c00, v245
	global_store_dword v217, v154, s[4:5]
	s_branch .LBB0_516
